# glu phase: pooling split 0.8 / 0.2 between the workgroups without and with a GLU tile (was 5/6 : 1/6)
# baseline (speedup 1.0000x reference)
; __device__ __forceinline__ int lane_id_v() { int l; asm volatile("v_mbcnt_lo_u32_b32 %0, -1, 0\n\tv_mbcnt_hi_u32_b32 %0, -1, %0" : "=v"(l)); return l; }
; #define LAS __attribute__((address_space(3)))
; __global__ void __launch_bounds__(512, 2) mega(Args a_unused) {
;     ...
;     const int wave_s = __builtin_amdgcn_readfirstlane((int)threadIdx.x >> 6);
;     volatile LAS unsigned* bst = (volatile LAS unsigned*)(lds + 135168);
;     if (threadIdx.x < 2) bst[threadIdx.x] = 0u;
;     __syncthreads();
;     XcdBarrier xbar = xcd_barrier_post((unsigned*)(((ArgsP)__builtin_amdgcn_kernarg_segment_ptr())->ws), bst);
;     const int ph_lo = ((ArgsP)__builtin_amdgcn_kernarg_segment_ptr())->ph_lo, ph_hi = ((ArgsP)__builtin_amdgcn_kernarg_segment_ptr())->ph_hi;
;     for (int ph = ph_lo; ph < ph_hi; ++ph) {
;         const int kk9 = (ph - 2) % 9;
;         const int cls = ph == 0 ? 0 : ph == 1 ? 1 : ph == NPHASE - 1 ? 10 : (kk9 == 0 || kk9 == 6) ? 2 : kk9 == 1 ? 3 : kk9 == 2 ? 4 : kk9 == 3 ? 5 : kk9 == 4 ? 6 : kk9 == 5 ? 7 : kk9 == 7 ? 8 : 9;
;         const int nrep = 1 + ((REPM >> cls) & 1);
;         for (int rep = 0; rep < nrep; ++rep) {
;         ArgsP a = (ArgsP)__builtin_amdgcn_kernarg_segment_ptr(); asm volatile("" : "+s"(a));
;         int G = gridDim.x, c = blockIdx.x; asm volatile("" : "+s"(G), "+s"(c));
;         int tid = wave_s * 64 + lane_id_v(); asm volatile("" : "+v"(tid));
;         unsigned char* ws = a->ws;
;     ...
;                   if (G > 132) { constexpr int SPLIT = (NI / 6 * 5) & ~63;
;                       if (c >= 132) pool_phase(a, l, XAp, Dp, (c - 132) * 512 + t_, (G - 132) * 512, 0, SPLIT, true);
;                       else pool_phase(a, l, XAp, Dp, c * 512 + t_, 132 * 512, SPLIT, NI, false); }
.LBB0_6:
	s_and_b32 s2, s76, 7
	s_lshr_b32 s3, s82, 3
	s_mul_i32 s2, s3, s2
	s_lshr_b32 s3, s76, 3
	s_and_b32 s90, s4, 0xffffffc0
	s_mul_i32 s0, s83, s82
	s_lshl_b32 s83, s76, 3
	s_lshl_b32 s48, s82, 3
	s_lshl_b32 s91, s76, 9
	s_lshl_b32 s50, s82, 9
	s_and_b32 s1, s82, 7
	s_load_dword s5, s[78:79], 0x168
	s_add_i32 s2, s2, s3
	s_cmpk_lt_i32 s87, 0x3e9
	s_cselect_b64 s[6:7], -1, 0
	s_cmp_eq_u32 s1, 0
	s_cselect_b32 s95, s2, s76
	v_writelane_b32 v254, s6, 4
	s_cmpk_lt_i32 s95, 0x100
	s_waitcnt lgkmcnt(0)
	s_mul_i32 s92, s0, s5
	v_writelane_b32 v254, s7, 5
	s_cselect_b64 s[0:1], -1, 0
	v_writelane_b32 v254, s0, 6
	v_lshrrev_b32_e32 v2, 20, v0
	v_lshrrev_b32_e32 v0, 10, v0
	v_writelane_b32 v254, s1, 7
	s_lshl_b32 s0, s76, 10
	v_writelane_b32 v254, s0, 8
	s_lshl_b32 s0, s4, 2
	s_and_b32 s0, s0, 0xffffff00
	v_writelane_b32 v254, s0, 9
	s_add_i32 s0, s90, 0x22b00
	v_writelane_b32 v254, s0, 10
	s_flbit_i32_b32 s0, 0
	s_min_u32 s65, s0, 32
	s_add_i32 s0, 0, 0x9000
	v_writelane_b32 v254, s0, 11
	s_add_i32 s0, 0, 0x11000
	v_writelane_b32 v254, s0, 12
	s_add_i32 s0, 0, 0x11180
	v_or_b32_e32 v0, v0, v2
	s_movk_i32 s93, 0x3ff
	v_writelane_b32 v254, s0, 13
	s_add_i32 s0, 0, 0x21000
	v_and_or_b32 v0, v0, s93, v1
	v_writelane_b32 v254, s0, 14
	s_add_i32 s0, 0, 0x21004
	v_writelane_b32 v254, s0, 15
	v_cmp_eq_u32_e64 s[0:1], 0, v0
	s_ashr_i32 s51, s50, 31
	s_lshl_b32 s84, s82, 10
	v_writelane_b32 v254, s0, 16
	v_mbcnt_lo_u32_b32 v1, -1, 0
	s_ashr_i32 s49, s48, 31
	v_writelane_b32 v254, s1, 17
	s_lshl_b64 s[0:1], s[50:51], 1
	v_writelane_b32 v254, s0, 18
	v_mov_b32_e32 v97, 0
	s_movk_i32 s96, 0x200
	v_writelane_b32 v254, s1, 19
	s_lshl_b64 s[0:1], s[50:51], 4
	v_writelane_b32 v254, s0, 20
	s_mov_b32 s97, 0x200000
	s_mov_b32 s75, 0x400000
	v_writelane_b32 v254, s1, 21
	s_mov_b32 s74, 0x600000
	s_mov_b32 s42, 0x800000
	s_mov_b32 s72, 0xa00000
	s_mov_b32 s73, 0xc00000
	s_mov_b32 s46, 0xe00000
	s_mov_b32 s60, 0x1000000
	s_mov_b32 s70, 0x1200000
	s_mov_b32 s71, 0x1400000
	s_movk_i32 s61, 0x1800
	s_movk_i32 s64, 0x1600
	v_mov_b32_e32 v195, 0xff800000
	v_mbcnt_hi_u32_b32 v196, -1, v1
	v_mov_b32_e32 v197, 0x7f800000
	s_movk_i32 s66, 0x84
	s_mov_b32 s67, 0xff800000
	s_movk_i32 s94, 0x7fff
	s_movk_i32 s47, 0x1300
	s_mov_b32 s57, 0
	s_lshl_b64 s[58:59], s[50:51], 2
	s_lshl_b64 s[62:63], s[50:51], 6
	s_mov_b64 s[68:69], 0x80
	v_writelane_b32 v254, s84, 22
	s_mov_b32 s100, 0
	s_branch .LBB0_11

; __device__ __forceinline__ int lane_id_v() { int l; asm volatile("v_mbcnt_lo_u32_b32 %0, -1, 0\n\tv_mbcnt_hi_u32_b32 %0, -1, %0" : "=v"(l)); return l; }
; DI void pool_phase(ArgsP a, int l, const float* XA, bf16_t* Dm, int gt  , int NT  , int lo, int hi  , bool do_sample) {
;     constexpr int NRUN = MP / 8;
;     for (int item = lo + gt; item < hi; item += NT) {
;         const int c4l = item & 31, gr = item >> 5, g = gr / NRUN, run = gr - g * NRUN; const int c4 = g * 128 + c4l * 4, row0 = run * 8;
; __global__ void __launch_bounds__(512, 2) mega(Args a_unused) {
;     ...
;                   constexpr int NI = 4 * (MP / 8) * 32; const float* XAp = (const float*)(ws + WS_XA); bf16_t* Dp = (bf16_t*)(ws + WS_DYY); const int t_ = wave_s * 64 + lane_id_v();
;                   if (G > 132) { constexpr int SPLIT = (NI / 6 * 5) & ~63;
;                       if (c >= 132) pool_phase(a, l, XAp, Dp, (c - 132) * 512 + t_, (G - 132) * 512, 0, SPLIT, true);
;                       else pool_phase(a, l, XAp, Dp, c * 512 + t_, 132 * 512, SPLIT, NI, false); }
.LBB0_612:
	s_and_b64 vcc, exec, s[4:5]
	s_cbranch_vccz .LBB0_878
	s_lshl_b32 s28, s38, 9
	s_cmpk_lt_i32 s38, 0x84
	s_mov_b64 s[4:5], -1
	s_cbranch_scc0 .LBB0_742
	v_add_u32_e32 v0, s28, v114
	s_mov_b32 s4, 0xcd00
	v_cmp_gt_i32_e32 vcc, s4, v0
	s_and_saveexec_b64 s[4:5], vcc
	s_cbranch_execz .LBB0_741
	s_add_u32 s10, s24, 0x4600000
	v_readlane_b32 s6, v254, 10
	s_addc_u32 s11, s25, 0
	s_add_i32 s6, s28, s6
	v_mov_b32_e32 v1, 0xccc00
	v_add_u32_e32 v96, s6, v115
	v_lshl_add_u32 v115, v0, 2, v1
	s_mov_b64 s[12:13], 0
	s_branch .LBB0_617

; __device__ __forceinline__ int lane_id_v() { int l; asm volatile("v_mbcnt_lo_u32_b32 %0, -1, 0\n\tv_mbcnt_hi_u32_b32 %0, -1, %0" : "=v"(l)); return l; }
; DI void pool_phase(ArgsP a, int l, const float* XA, bf16_t* Dm, int gt  , int NT  , int lo, int hi  , bool do_sample) {
;     constexpr int NRUN = MP / 8;
;     for (int item = lo + gt; item < hi; item += NT) {
;         const int c4l = item & 31, gr = item >> 5, g = gr / NRUN, run = gr - g * NRUN; const int c4 = g * 128 + c4l * 4, row0 = run * 8;
; __global__ void __launch_bounds__(512, 2) mega(Args a_unused) {
;     ...
;                   constexpr int NI = 4 * (MP / 8) * 32; const float* XAp = (const float*)(ws + WS_XA); bf16_t* Dp = (bf16_t*)(ws + WS_DYY); const int t_ = wave_s * 64 + lane_id_v();
;                   if (G > 132) { constexpr int SPLIT = (NI / 6 * 5) & ~63;
;                       if (c >= 132) pool_phase(a, l, XAp, Dp, (c - 132) * 512 + t_, (G - 132) * 512, 0, SPLIT, true);
;                       else pool_phase(a, l, XAp, Dp, c * 512 + t_, 132 * 512, SPLIT, NI, false); }
.LBB0_742:
	s_andn2_b64 vcc, exec, s[4:5]
	s_cbranch_vccnz .LBB0_878
	s_add_i32 s28, s28, 0xfffef800
	v_add_u32_e32 v114, s28, v114
	s_lshl_b32 s28, s51, 9
	s_mov_b32 s4, 0x33300
	s_add_i32 s28, s28, 0xfffef800
	v_cmp_gt_i32_e32 vcc, s4, v114
	s_and_saveexec_b64 s[4:5], vcc
	s_cbranch_execz .LBB0_870
	s_add_u32 s10, s24, 0x4600000
	s_addc_u32 s11, s25, 0
	s_lshl_b32 s29, s51, 11
	v_lshlrev_b32_e32 v96, 2, v114
	s_add_i32 s29, s29, 0xfffbe000
	s_mov_b64 s[12:13], 0
	v_mov_b32_e32 v115, v114
	s_branch .LBB0_746
.LBB0_745:
	s_or_b64 exec, exec, s[8:9]
	v_add_u32_e32 v115, s28, v115
	s_mov_b32 s6, 0x332ff
	v_cmp_lt_i32_e32 vcc, s6, v115
	s_or_b64 s[12:13], vcc, s[12:13]
	v_add_u32_e32 v96, s29, v96
	s_andn2_b64 exec, exec, s[12:13]
	s_cbranch_execz .LBB0_870
